# static s_setprio 1 for waves 0-3 at kernel entry, all per-segment s_setprio flips removed (strategy 7.4, other half)
# speedup vs baseline: 1.0067x; 1.0067x over previous
; #define LAS __attribute__((address_space(3)))
; __global__ void __launch_bounds__(NWAVES * 64, 2) hymba_fwd(Args args) {
;     extern __shared__ __attribute__((aligned(16))) unsigned char lds_raw[];
;     LAS unsigned char* lds = (LAS unsigned char*)lds_raw;
;     volatile LAS unsigned* MISC = (volatile LAS unsigned*)(lds + MISC_OFF);
;     const int tid = threadIdx.x, lane = tid & 63, wave = __builtin_amdgcn_readfirstlane(tid >> 6);
_Z9hymba_fwd4Args:
	v_readfirstlane_b32 s99, v0
	s_nop 3
	s_and_b32 s99, s99, 0x3ff
	s_lshr_b32 s99, s99, 6
	s_cmp_lt_u32 s99, 4
	s_cbranch_scc0 .Lprio_static_done
	s_setprio 1
